# ad1 + half of the waves (HW wave-slot parity) delayed by s_sleep 127 at the entry of the modulate0 / rowpass1 / rowpass2 row loops to break load-compute-store lockstep
# speedup vs baseline: 1.0049x; 1.0010x over previous
.LBB0_195:
	s_mov_b64 s[6:7], s[78:79]
	s_waitcnt lgkmcnt(0)
	s_barrier
	v_mbcnt_lo_u32_b32 v0, -1, 0
	v_mbcnt_hi_u32_b32 v0, -1, v0
	s_lshr_b32 s3, s3, 6
	v_add_u32_e32 v2, s66, v0
	s_load_dwordx2 s[4:5], s[6:7], 0xd0
	v_ashrrev_i32_e32 v0, 10, v2
	v_mul_hi_i32_i24_e32 v1, 0xc000, v0
	v_mul_i32_i24_e32 v0, 0xc000, v0
	v_lshlrev_b32_e32 v45, 4, v2
	s_waitcnt lgkmcnt(0)
	s_add_u32 s8, s4, 0x100000
	s_addc_u32 s9, s5, 0
	v_lshl_add_u64 v[4:5], s[8:9], 0, v[0:1]
	v_and_b32_e32 v0, 0x3ff0, v45
	v_mov_b32_e32 v1, 0
	v_add_u32_e32 v3, 0x200, v2
	v_lshl_add_u64 v[12:13], v[4:5], 0, v[0:1]
	v_ashrrev_i32_e32 v4, 10, v3
	v_lshlrev_b32_e32 v3, 4, v3
	v_mul_hi_i32_i24_e32 v5, 0xc000, v4
	v_mul_i32_i24_e32 v4, 0xc000, v4
	v_and_b32_e32 v6, 0x3ff0, v3
	v_add_u32_e32 v3, 0x400, v2
	v_lshl_add_u64 v[4:5], s[8:9], 0, v[4:5]
	v_mov_b32_e32 v7, v1
	v_ashrrev_i32_e32 v3, 10, v3
	v_lshl_add_u64 v[14:15], v[4:5], 0, v[6:7]
	global_load_dwordx4 v[4:7], v[12:13], off
	global_load_dwordx4 v[8:11], v[14:15], off
	v_mul_hi_i32_i24_e32 v13, 0xc000, v3
	v_mul_i32_i24_e32 v12, 0xc000, v3
	v_lshl_add_u64 v[12:13], s[8:9], 0, v[12:13]
	v_add_u32_e32 v3, 0x600, v2
	v_lshl_add_u64 v[20:21], v[12:13], 0, v[0:1]
	v_ashrrev_i32_e32 v12, 10, v3
	v_mul_hi_i32_i24_e32 v13, 0xc000, v12
	v_mul_i32_i24_e32 v12, 0xc000, v12
	v_lshlrev_b32_e32 v3, 4, v3
	v_add_u32_e32 v44, 0x800, v2
	v_lshl_add_u64 v[12:13], s[8:9], 0, v[12:13]
	v_and_b32_e32 v14, 0x3ff0, v3
	v_mov_b32_e32 v15, v1
	v_ashrrev_i32_e32 v3, 10, v44
	v_lshl_add_u64 v[22:23], v[12:13], 0, v[14:15]
	global_load_dwordx4 v[12:15], v[20:21], off
	global_load_dwordx4 v[16:19], v[22:23], off
	v_mul_hi_i32_i24_e32 v21, 0xc000, v3
	v_mul_i32_i24_e32 v20, 0xc000, v3
	v_lshl_add_u64 v[20:21], s[8:9], 0, v[20:21]
	v_add_u32_e32 v3, 0xa00, v2
	v_lshl_add_u64 v[28:29], v[20:21], 0, v[0:1]
	v_ashrrev_i32_e32 v20, 10, v3
	v_lshlrev_b32_e32 v3, 4, v3
	v_mul_hi_i32_i24_e32 v21, 0xc000, v20
	v_mul_i32_i24_e32 v20, 0xc000, v20
	v_and_b32_e32 v22, 0x3ff0, v3
	v_add_u32_e32 v3, 0xc00, v2
	v_lshl_add_u64 v[20:21], s[8:9], 0, v[20:21]
	v_mov_b32_e32 v23, v1
	v_ashrrev_i32_e32 v3, 10, v3
	v_lshl_add_u64 v[30:31], v[20:21], 0, v[22:23]
	global_load_dwordx4 v[20:23], v[28:29], off
	global_load_dwordx4 v[24:27], v[30:31], off
	v_mul_hi_i32_i24_e32 v29, 0xc000, v3
	v_mul_i32_i24_e32 v28, 0xc000, v3
	v_lshl_add_u64 v[28:29], s[8:9], 0, v[28:29]
	v_add_u32_e32 v3, 0xe00, v2
	v_lshl_add_u64 v[36:37], v[28:29], 0, v[0:1]
	v_ashrrev_i32_e32 v28, 10, v3
	v_lshlrev_b32_e32 v3, 4, v3
	v_mul_hi_i32_i24_e32 v29, 0xc000, v28
	v_mul_i32_i24_e32 v28, 0xc000, v28
	v_and_b32_e32 v30, 0x3ff0, v3
	v_add_u32_e32 v3, 0x1000, v2
	v_lshl_add_u64 v[28:29], s[8:9], 0, v[28:29]
	v_mov_b32_e32 v31, v1
	v_ashrrev_i32_e32 v3, 10, v3
	v_lshl_add_u64 v[38:39], v[28:29], 0, v[30:31]
	global_load_dwordx4 v[28:31], v[36:37], off
	global_load_dwordx4 v[32:35], v[38:39], off
	v_mul_hi_i32_i24_e32 v37, 0xc000, v3
	v_mul_i32_i24_e32 v36, 0xc000, v3
	v_lshl_add_u64 v[36:37], s[8:9], 0, v[36:37]
	v_lshl_add_u64 v[36:37], v[36:37], 0, v[0:1]
	v_add_u32_e32 v3, 0x1200, v2
	global_load_dwordx4 v[36:39], v[36:37], off
	v_ashrrev_i32_e32 v40, 10, v3
	v_mul_hi_i32_i24_e32 v41, 0xc000, v40
	v_mul_i32_i24_e32 v40, 0xc000, v40
	v_lshlrev_b32_e32 v3, 4, v3
	v_lshl_add_u64 v[40:41], s[8:9], 0, v[40:41]
	v_and_b32_e32 v42, 0x3ff0, v3
	v_mov_b32_e32 v43, v1
	v_lshl_add_u64 v[40:41], v[40:41], 0, v[42:43]
	global_load_dwordx4 v[40:43], v[40:41], off
	v_and_b32_e32 v45, 0xffffc000, v45
	v_add3_u32 v0, 0, v45, v0
	v_lshlrev_b32_e32 v3, 2, v2
	v_readlane_b32 s8, v253, 0
	s_add_i32 s8, s3, s8
	s_cmpk_lt_i32 s8, 0x4400
	s_mov_b32 s9, 0
	s_mov_b32 s38, s8
	s_waitcnt vmcnt(0)
	ds_write_b128 v0, v[4:7]
	v_mad_u64_u32 v[4:5], s[10:11], v2, 3, v[44:45]
	v_and_b32_e32 v5, 0xffc, v4
	v_and_b32_e32 v4, 0x3ffff000, v4
	v_lshlrev_b32_e32 v4, 2, v4
	v_lshlrev_b32_e32 v5, 2, v5
	v_add3_u32 v4, 0, v4, v5
	ds_write_b128 v4, v[8:11]
	ds_write_b128 v0, v[12:15] offset:16384
	v_add_u32_e32 v4, 0x1800, v3
	v_and_b32_e32 v5, 0xffc, v4
	v_and_b32_e32 v4, 0x3ffff000, v4
	v_lshlrev_b32_e32 v4, 2, v4
	v_lshlrev_b32_e32 v5, 2, v5
	v_add3_u32 v4, 0, v4, v5
	ds_write_b128 v4, v[16:19]
	ds_write_b128 v0, v[20:23] offset:32768
	v_add_u32_e32 v4, 0x2800, v3
	v_and_b32_e32 v5, 0xffc, v4
	v_and_b32_e32 v4, 0x3ffff000, v4
	v_lshlrev_b32_e32 v4, 2, v4
	v_lshlrev_b32_e32 v5, 2, v5
	v_add3_u32 v4, 0, v4, v5
	ds_write_b128 v4, v[24:27]
	ds_write_b128 v0, v[28:31] offset:49152
	v_add_u32_e32 v4, 0x3800, v3
	v_and_b32_e32 v5, 0xffc, v4
	v_and_b32_e32 v4, 0x3ffff000, v4
	v_lshlrev_b32_e32 v4, 2, v4
	v_lshlrev_b32_e32 v5, 2, v5
	v_add3_u32 v4, 0, v4, v5
	v_add_u32_e32 v0, 0x10000, v0
	ds_write_b128 v4, v[32:35]
	ds_write_b128 v0, v[36:39]
	v_add_u32_e32 v0, 0x4800, v3
	v_and_b32_e32 v4, 0xffc, v0
	v_and_b32_e32 v0, 0x3ffff000, v0
	s_cselect_b64 s[10:11], -1, 0
	v_lshlrev_b32_e32 v0, 2, v0
	v_lshlrev_b32_e32 v4, 2, v4
	v_writelane_b32 v253, s10, 2
	v_add3_u32 v0, 0, v0, v4
	s_cmpk_gt_i32 s8, 0x43ff
	v_writelane_b32 v253, s11, 3
	ds_write_b128 v0, v[40:43]
	s_waitcnt lgkmcnt(0)
	s_barrier
	s_cbranch_scc1 .LBB0_210
	v_and_b32_e32 v64, 0xfc, v3
	v_bfrev_b32_e32 v0, 0.5
	s_movk_i32 s3, 0x80
	v_bitop3_b32 v65, v3, 4, v0 bitop3:0x6c
	v_bitop3_b32 v72, v3, 8, v0 bitop3:0x6c
	v_bitop3_b32 v73, v3, 16, v0 bitop3:0x6c
	v_bitop3_b32 v74, v3, 32, v0 bitop3:0x6c
	v_bitop3_b32 v75, v3, 64, v0 bitop3:0x6c
	v_bitop3_b32 v76, v3, s3, v0 bitop3:0x6c
	s_lshl_b32 s10, s80, 4
	v_lshlrev_b32_e32 v0, 1, v64
	v_lshl_add_u64 v[12:13], s[4:5], 0, v[0:1]
	s_mov_b64 s[12:13], 0xc800000
	s_mov_b32 s20, s38
	s_ashr_i32 s21, s38, 31
	s_ashr_i32 s11, s10, 31
	v_lshl_add_u64 v[66:67], v[12:13], 0, s[12:13]
	s_lshl_b64 s[12:13], s[20:21], 13
	s_lshl_b64 s[14:15], s[10:11], 13
	s_lshl_b64 s[18:19], s[20:21], 12
	v_and_b32_e32 v0, 63, v2
	s_add_u32 s4, s4, s18
	v_lshlrev_b32_e32 v0, 3, v0
	s_addc_u32 s5, s5, s19
	v_or_b32_e32 v4, 0x400, v64
	v_or_b32_e32 v6, 0x500, v64
	v_or_b32_e32 v8, 0x600, v64
	v_or_b32_e32 v10, 0x700, v64
	s_mov_b64 s[16:17], 0x15000000
	v_lshl_add_u64 v[0:1], s[4:5], 0, v[0:1]
	v_lshl_add_u32 v77, v64, 2, 0
	v_lshl_add_u64 v[68:69], v[12:13], 0, s[16:17]
	v_lshl_add_u64 v[70:71], v[0:1], 0, s[16:17]
	s_lshl_b64 s[16:17], s[10:11], 12
	s_mov_b64 s[18:19], 0
	v_lshlrev_b32_e32 v78, 2, v4
	v_lshlrev_b32_e32 v79, 2, v6
	v_lshlrev_b32_e32 v80, 2, v8
	v_lshlrev_b32_e32 v81, 2, v10
	v_mov_b32_e32 v82, 0x358637bd
	s_mov_b32 s3, 0xf800000
	v_mov_b32_e32 v83, 0x260
	s_movk_i32 s28, 0x7fff
	s_mov_b32 s29, 0xffff0000
	s_mov_b64 s[38:39], s[20:21]
	s_getreg_b32 s100, hwreg(HW_REG_HW_ID, 0, 1)
	s_cmp_eq_u32 s100, 1
	s_cbranch_scc0 .Lstag_skip1
	s_sleep 127
.Lstag_skip1:
	s_branch .LBB0_198

.LBB0_916:
	s_mov_b64 s[0:1], s[78:79]
	s_waitcnt lgkmcnt(0)
	s_barrier
	v_mbcnt_lo_u32_b32 v0, -1, 0
	v_mbcnt_hi_u32_b32 v0, -1, v0
	v_writelane_b32 v255, s54, 9
	v_add_u32_e32 v64, s66, v0
	s_load_dwordx2 s[6:7], s[0:1], 0xd0
	s_load_dwordx4 s[16:19], s[0:1], 0x80
	v_writelane_b32 v255, s55, 10
	v_readlane_b32 s36, v253, 56
	v_readlane_b32 s4, v255, 5
	s_lshl_b32 s8, s4, 11
	s_mov_b32 s9, s36
	s_lshl_b64 s[64:65], s[8:9], 2
	s_waitcnt lgkmcnt(0)
	s_add_u32 s8, s16, s64
	v_lshlrev_b32_e32 v0, 2, v64
	s_addc_u32 s9, s17, s65
	v_ashrrev_i32_e32 v1, 31, v0
	s_add_u32 s14, s18, s64
	v_lshlrev_b64 v[10:11], 2, v[0:1]
	s_addc_u32 s15, s19, s65
	v_lshl_add_u64 v[2:3], s[8:9], 0, v[10:11]
	global_load_dwordx4 v[2:5], v[2:3], off
	v_lshl_add_u64 v[6:7], s[14:15], 0, v[10:11]
	global_load_dwordx4 v[6:9], v[6:7], off
	v_readlane_b32 s50, v254, 6
	v_readlane_b32 s51, v254, 7
	s_mul_i32 s8, s4, 0xf000
	s_mov_b32 s9, s36
	s_lshl_b64 s[50:51], s[8:9], 2
	s_add_u32 s8, s6, s50
	s_addc_u32 s9, s7, s51
	v_lshl_add_u32 v1, v64, 4, 0
	v_lshl_add_u64 v[46:47], s[8:9], 0, v[10:11]
	s_mov_b32 s8, 0x104000
	v_readlane_b32 s5, v255, 6
	v_readlane_b32 s37, v253, 57
	v_readlane_b32 s38, v253, 58
	v_readlane_b32 s39, v253, 59
	v_readlane_b32 s40, v253, 60
	v_readlane_b32 s41, v253, 61
	v_readlane_b32 s42, v253, 62
	v_readlane_b32 s43, v253, 63
	v_readlane_b32 s44, v254, 0
	v_readlane_b32 s45, v254, 1
	v_readlane_b32 s46, v254, 2
	v_readlane_b32 s47, v254, 3
	v_readlane_b32 s48, v254, 4
	v_readlane_b32 s49, v254, 5
	s_waitcnt vmcnt(0)
	ds_write_b128 v1, v[2:5]
	ds_write_b128 v1, v[6:9] offset:8192
	v_add_co_u32_e32 v2, vcc, s8, v46
	s_mov_b32 s8, 0x106000
	s_nop 0
	v_addc_co_u32_e32 v3, vcc, 0, v47, vcc
	v_add_co_u32_e32 v6, vcc, s8, v46
	s_mov_b32 s8, 0x108000
	s_nop 0
	v_addc_co_u32_e32 v7, vcc, 0, v47, vcc
	v_add_co_u32_e32 v10, vcc, s8, v46
	s_mov_b32 s8, 0x110000
	s_nop 0
	v_addc_co_u32_e32 v11, vcc, 0, v47, vcc
	v_add_co_u32_e32 v14, vcc, s8, v46
	s_mov_b32 s8, 0x112000
	s_nop 0
	v_addc_co_u32_e32 v15, vcc, 0, v47, vcc
	v_add_co_u32_e32 v18, vcc, s8, v46
	s_mov_b32 s8, 0x114000
	s_nop 0
	v_addc_co_u32_e32 v19, vcc, 0, v47, vcc
	v_add_co_u32_e32 v22, vcc, s8, v46
	s_mov_b32 s8, 0x11c000
	s_nop 0
	v_addc_co_u32_e32 v23, vcc, 0, v47, vcc
	v_add_co_u32_e32 v26, vcc, s8, v46
	s_mov_b32 s8, 0x11e000
	s_nop 0
	v_addc_co_u32_e32 v27, vcc, 0, v47, vcc
	v_add_co_u32_e32 v30, vcc, s8, v46
	s_mov_b32 s8, 0x120000
	s_nop 0
	v_addc_co_u32_e32 v31, vcc, 0, v47, vcc
	v_add_co_u32_e32 v34, vcc, s8, v46
	s_mov_b32 s8, 0x128000
	s_nop 0
	v_addc_co_u32_e32 v35, vcc, 0, v47, vcc
	v_add_co_u32_e32 v38, vcc, s8, v46
	global_load_dwordx4 v[2:5], v[2:3], off
	s_nop 0
	v_addc_co_u32_e32 v39, vcc, 0, v47, vcc
	s_mov_b32 s8, 0x12a000
	global_load_dwordx4 v[6:9], v[6:7], off
	v_add_co_u32_e32 v42, vcc, s8, v46
	global_load_dwordx4 v[26:29], v[26:27], off
	s_nop 0
	v_addc_co_u32_e32 v43, vcc, 0, v47, vcc
	global_load_dwordx4 v[10:13], v[10:11], off
	s_mov_b32 s8, 0x12c000
	global_load_dwordx4 v[30:33], v[30:31], off
	v_add_co_u32_e32 v46, vcc, s8, v46
	global_load_dwordx4 v[14:17], v[14:15], off
	s_nop 0
	v_addc_co_u32_e32 v47, vcc, 0, v47, vcc
	global_load_dwordx4 v[34:37], v[34:35], off
	v_readlane_b32 s8, v253, 34
	global_load_dwordx4 v[18:21], v[18:19], off
	v_readlane_b32 s9, v253, 35
	global_load_dwordx4 v[38:41], v[38:39], off
	s_andn2_b64 vcc, exec, s[8:9]
	global_load_dwordx4 v[22:25], v[22:23], off
	s_nop 0
	global_load_dwordx4 v[42:45], v[42:43], off
	s_nop 0
	global_load_dwordx4 v[46:49], v[46:47], off
	s_waitcnt vmcnt(11)
	ds_write_b128 v1, v[2:5] offset:16384
	s_waitcnt vmcnt(10)
	ds_write_b128 v1, v[6:9] offset:24576
	s_waitcnt vmcnt(8)
	ds_write_b128 v1, v[10:13] offset:32768
	s_waitcnt vmcnt(6)
	ds_write_b128 v1, v[14:17] offset:40960
	s_waitcnt vmcnt(4)
	ds_write_b128 v1, v[18:21] offset:49152
	s_waitcnt vmcnt(2)
	ds_write_b128 v1, v[22:25] offset:57344
	v_add_u32_e32 v2, 0x10000, v1
	ds_write_b128 v2, v[26:29]
	v_add_u32_e32 v2, 0x12000, v1
	ds_write_b128 v2, v[30:33]
	v_add_u32_e32 v2, 0x14000, v1
	ds_write_b128 v2, v[34:37]
	v_add_u32_e32 v2, 0x16000, v1
	ds_write_b128 v2, v[38:41]
	v_add_u32_e32 v2, 0x18000, v1
	v_add_u32_e32 v1, 0x1a000, v1
	s_waitcnt vmcnt(0)
	ds_write_b128 v1, v[46:49]
	v_cndmask_b32_e64 v1, 0, 1, s[8:9]
	v_cmp_ne_u32_e64 s[4:5], 1, v1
	ds_write_b128 v2, v[42:45]
	s_waitcnt lgkmcnt(0)
	v_writelane_b32 v255, s4, 41
	s_barrier
	s_nop 0
	v_writelane_b32 v255, s5, 42
	s_cbranch_vccnz .LBB0_923
	v_and_b32_e32 v65, 0xfc, v0
	v_bfrev_b32_e32 v1, 0.5
	s_movk_i32 s4, 0x80
	v_lshl_add_u32 v176, v65, 2, 0
	v_bitop3_b32 v170, v0, 4, v1 bitop3:0x6c
	v_bitop3_b32 v171, v0, 8, v1 bitop3:0x6c
	v_bitop3_b32 v172, v0, 16, v1 bitop3:0x6c
	v_bitop3_b32 v173, v0, 32, v1 bitop3:0x6c
	v_bitop3_b32 v174, v0, 64, v1 bitop3:0x6c
	v_bitop3_b32 v175, v0, s4, v1 bitop3:0x6c
	ds_read_b128 v[0:3], v176
	ds_read_b128 v[4:7], v176 offset:1024
	ds_read_b128 v[8:11], v176 offset:8192
	ds_read_b128 v[12:15], v176 offset:9216
	ds_read_b128 v[16:19], v176 offset:2048
	ds_read_b128 v[20:23], v176 offset:3072
	ds_read_b128 v[24:27], v176 offset:10240
	ds_read_b128 v[28:31], v176 offset:11264
	ds_read_b128 v[32:35], v176 offset:4096
	ds_read_b128 v[36:39], v176 offset:5120
	ds_read_b128 v[40:43], v176 offset:12288
	ds_read_b128 v[44:47], v176 offset:13312
	ds_read_b128 v[48:51], v176 offset:6144
	ds_read_b128 v[52:55], v176 offset:7168
	ds_read_b128 v[56:59], v176 offset:14336
	ds_read_b128 v[60:63], v176 offset:15360
	v_lshlrev_b32_e32 v144, 1, v65
	v_lshl_add_u64 v[66:67], s[6:7], 0, v[144:145]
	s_mov_b64 s[4:5], 0x19400000
	v_lshl_add_u64 v[128:129], v[66:67], 0, s[4:5]
	s_mov_b64 s[4:5], 0x15000000
	v_lshl_add_u64 v[132:133], v[66:67], 0, s[4:5]
	v_readlane_b32 s4, v254, 24
	s_add_u32 s6, s6, s4
	v_readlane_b32 s4, v254, 27
	v_and_b32_e32 v64, 63, v64
	s_addc_u32 s7, s7, s4
	v_lshlrev_b32_e32 v144, 3, v64
	s_mov_b64 s[14:15], 0xc800000
	v_lshl_add_u64 v[134:135], s[6:7], 0, v[144:145]
	v_readlane_b32 s6, v254, 28
	s_mov_b32 s8, 0xf7800000
	s_mov_b32 s10, 0xf7800200
	s_mov_b32 s12, 0xf7800400
	s_mov_b32 s20, 0xf7800600
	s_mov_b32 s22, 0xf7800800
	s_mov_b32 s24, 0xf7800a00
	s_mov_b32 s26, 0xf7800c00
	s_mov_b32 s28, 0xf7800e00
	v_lshl_add_u64 v[130:131], v[66:67], 0, s[14:15]
	s_mov_b32 s18, s6
	s_mov_b32 s4, 0xffff0000
	s_mov_b32 s5, 0xf800000
	s_mov_b32 s9, -1
	s_mov_b32 s11, -1
	s_mov_b32 s13, -1
	s_mov_b32 s21, -1
	s_mov_b32 s23, -1
	s_mov_b32 s25, -1
	s_mov_b32 s27, -1
	s_mov_b32 s29, -1
	s_mov_b32 s30, 0x3fb504f3
	v_readlane_b32 s7, v254, 29
	s_getreg_b32 s100, hwreg(HW_REG_HW_ID, 0, 1)
	s_cmp_eq_u32 s100, 1
	s_cbranch_scc0 .Lstag_skip2
	s_sleep 127

.LBB0_1223:
	s_mov_b64 s[10:11], s[78:79]
	s_waitcnt lgkmcnt(0)
	s_barrier
	v_mbcnt_lo_u32_b32 v0, -1, 0
	v_mbcnt_hi_u32_b32 v0, -1, v0
	s_mov_b32 s6, 0x10a000
	v_add_u32_e32 v64, s66, v0
	s_load_dwordx4 s[12:15], s[10:11], 0xb8
	s_load_dwordx2 s[16:17], s[10:11], 0xd0
	v_lshlrev_b32_e32 v0, 2, v64
	v_ashrrev_i32_e32 v1, 31, v0
	v_lshlrev_b64 v[10:11], 2, v[0:1]
	s_waitcnt lgkmcnt(0)
	s_add_u32 s12, s12, s64
	s_addc_u32 s13, s13, s65
	s_add_u32 s14, s14, s64
	s_addc_u32 s15, s15, s65
	v_lshl_add_u64 v[2:3], s[12:13], 0, v[10:11]
	global_load_dwordx4 v[2:5], v[2:3], off
	v_lshl_add_u64 v[6:7], s[14:15], 0, v[10:11]
	global_load_dwordx4 v[6:9], v[6:7], off
	s_add_u32 s12, s16, s50
	s_addc_u32 s13, s17, s51
	v_lshl_add_u32 v1, v64, 4, 0
	v_lshl_add_u64 v[38:39], s[12:13], 0, v[10:11]
	v_lshl_add_u64 v[46:47], s[16:17], 0, v[10:11]
	v_readlane_b32 s4, v255, 41
	v_readlane_b32 s5, v255, 42
	s_waitcnt vmcnt(0)
	ds_write_b128 v1, v[2:5]
	ds_write_b128 v1, v[6:9] offset:8192
	v_add_co_u32_e32 v2, vcc, s6, v38
	s_mov_b32 s6, 0x13c000
	s_nop 0
	v_addc_co_u32_e32 v3, vcc, 0, v39, vcc
	v_add_co_u32_e32 v6, vcc, s6, v46
	s_mov_b32 s6, 0x13e000
	s_nop 0
	v_addc_co_u32_e32 v7, vcc, 0, v47, vcc
	v_add_co_u32_e32 v10, vcc, s6, v46
	s_mov_b32 s6, 0x116000
	s_nop 0
	v_addc_co_u32_e32 v11, vcc, 0, v47, vcc
	v_add_co_u32_e32 v14, vcc, s6, v38
	s_mov_b32 s6, 0x148000
	s_nop 0
	v_addc_co_u32_e32 v15, vcc, 0, v39, vcc
	v_add_co_u32_e32 v18, vcc, s6, v46
	s_mov_b32 s6, 0x14a000
	s_nop 0
	v_addc_co_u32_e32 v19, vcc, 0, v47, vcc
	v_add_co_u32_e32 v22, vcc, s6, v46
	s_mov_b32 s6, 0x122000
	s_nop 0
	v_addc_co_u32_e32 v23, vcc, 0, v47, vcc
	v_add_co_u32_e32 v26, vcc, s6, v38
	s_mov_b32 s6, 0x154000
	s_nop 0
	v_addc_co_u32_e32 v27, vcc, 0, v39, vcc
	v_add_co_u32_e32 v30, vcc, s6, v46
	s_mov_b32 s6, 0x156000
	s_nop 0
	v_addc_co_u32_e32 v31, vcc, 0, v47, vcc
	v_add_co_u32_e32 v34, vcc, s6, v46
	s_mov_b32 s6, 0x12e000
	s_nop 0
	v_addc_co_u32_e32 v35, vcc, 0, v47, vcc
	v_add_co_u32_e32 v38, vcc, s6, v38
	global_load_dwordx4 v[2:5], v[2:3], off
	s_nop 0
	v_addc_co_u32_e32 v39, vcc, 0, v39, vcc
	s_mov_b32 s6, 0x160000
	global_load_dwordx4 v[6:9], v[6:7], off
	v_add_co_u32_e32 v42, vcc, s6, v46
	global_load_dwordx4 v[26:29], v[26:27], off
	s_nop 0
	v_addc_co_u32_e32 v43, vcc, 0, v47, vcc
	global_load_dwordx4 v[10:13], v[10:11], off
	s_mov_b32 s6, 0x162000
	global_load_dwordx4 v[30:33], v[30:31], off
	v_add_co_u32_e32 v46, vcc, s6, v46
	global_load_dwordx4 v[14:17], v[14:15], off
	s_nop 0
	v_addc_co_u32_e32 v47, vcc, 0, v47, vcc
	global_load_dwordx4 v[34:37], v[34:35], off
	s_and_b64 vcc, exec, s[4:5]
	global_load_dwordx4 v[18:21], v[18:19], off
	s_nop 0
	global_load_dwordx4 v[22:25], v[22:23], off
	s_nop 0
	global_load_dwordx4 v[38:41], v[38:39], off
	s_nop 0
	global_load_dwordx4 v[42:45], v[42:43], off
	s_nop 0
	global_load_dwordx4 v[46:49], v[46:47], off
	s_waitcnt vmcnt(11)
	ds_write_b128 v1, v[2:5] offset:16384
	s_waitcnt vmcnt(10)
	ds_write_b128 v1, v[6:9] offset:24576
	s_waitcnt vmcnt(8)
	ds_write_b128 v1, v[10:13] offset:32768
	s_waitcnt vmcnt(6)
	ds_write_b128 v1, v[14:17] offset:40960
	s_waitcnt vmcnt(4)
	ds_write_b128 v1, v[18:21] offset:49152
	s_waitcnt vmcnt(3)
	ds_write_b128 v1, v[22:25] offset:57344
	v_add_u32_e32 v2, 0x10000, v1
	ds_write_b128 v2, v[26:29]
	v_add_u32_e32 v2, 0x12000, v1
	ds_write_b128 v2, v[30:33]
	v_add_u32_e32 v2, 0x14000, v1
	ds_write_b128 v2, v[34:37]
	v_add_u32_e32 v2, 0x16000, v1
	s_waitcnt vmcnt(2)
	ds_write_b128 v2, v[38:41]
	v_add_u32_e32 v2, 0x18000, v1
	v_add_u32_e32 v1, 0x1a000, v1
	s_waitcnt vmcnt(1)
	ds_write_b128 v2, v[42:45]
	s_waitcnt vmcnt(0)
	ds_write_b128 v1, v[46:49]
	s_waitcnt lgkmcnt(0)
	s_barrier
	s_cbranch_vccnz .LBB0_1297
	v_and_b32_e32 v128, 0xfc, v0
	v_bfrev_b32_e32 v1, 0.5
	s_movk_i32 s4, 0x80
	v_lshl_add_u32 v187, v128, 2, 0
	v_bitop3_b32 v129, v0, 4, v1 bitop3:0x6c
	v_bitop3_b32 v182, v0, 8, v1 bitop3:0x6c
	v_bitop3_b32 v183, v0, 16, v1 bitop3:0x6c
	v_bitop3_b32 v184, v0, 32, v1 bitop3:0x6c
	v_bitop3_b32 v185, v0, 64, v1 bitop3:0x6c
	v_bitop3_b32 v186, v0, s4, v1 bitop3:0x6c
	s_load_dwordx2 s[14:15], s[10:11], 0xc8
	ds_read_b128 v[0:3], v187
	ds_read_b128 v[4:7], v187 offset:1024
	ds_read_b128 v[8:11], v187 offset:8192
	ds_read_b128 v[12:15], v187 offset:9216
	ds_read_b128 v[16:19], v187 offset:2048
	ds_read_b128 v[20:23], v187 offset:3072
	ds_read_b128 v[24:27], v187 offset:10240
	ds_read_b128 v[28:31], v187 offset:11264
	ds_read_b128 v[32:35], v187 offset:4096
	ds_read_b128 v[36:39], v187 offset:5120
	ds_read_b128 v[40:43], v187 offset:12288
	ds_read_b128 v[44:47], v187 offset:13312
	ds_read_b128 v[48:51], v187 offset:6144
	ds_read_b128 v[52:55], v187 offset:7168
	ds_read_b128 v[56:59], v187 offset:14336
	ds_read_b128 v[60:63], v187 offset:15360
	v_lshlrev_b32_e32 v144, 1, v128
	v_lshl_add_u64 v[74:75], s[16:17], 0, v[144:145]
	s_mov_b64 s[4:5], 0x19400000
	s_add_u32 s12, s16, 0xc800000
	v_lshl_add_u64 v[130:131], v[74:75], 0, s[4:5]
	s_mov_b64 s[4:5], 0x15000000
	s_addc_u32 s13, s17, 0
	v_lshl_add_u64 v[134:135], v[74:75], 0, s[4:5]
	v_readlane_b32 s4, v254, 24
	s_add_u32 s8, s16, s4
	v_readlane_b32 s4, v254, 27
	v_and_b32_e32 v64, 63, v64
	v_lshl_add_u64 v[132:133], s[12:13], 0, v[144:145]
	s_addc_u32 s9, s17, s4
	v_lshlrev_b32_e32 v144, 3, v64
	v_readlane_b32 s4, v254, 30
	v_lshl_add_u64 v[136:137], s[8:9], 0, v[144:145]
	v_readlane_b32 s5, v254, 31
	s_waitcnt lgkmcnt(0)
	s_add_u32 s8, s14, s4
	v_or_b32_e32 v66, 0x400, v128
	v_or_b32_e32 v68, 0x500, v128
	v_or_b32_e32 v70, 0x600, v128
	v_or_b32_e32 v72, 0x700, v128
	s_addc_u32 s9, s15, s5
	v_lshlrev_b32_e32 v144, 4, v64
	v_readlane_b32 s6, v254, 28
	v_lshl_add_u64 v[138:139], s[8:9], 0, v[144:145]
	v_lshlrev_b32_e32 v144, 2, v66
	v_lshlrev_b32_e32 v188, 2, v68
	v_lshlrev_b32_e32 v189, 2, v70
	v_lshlrev_b32_e32 v190, 2, v72
	s_mov_b32 s22, s6
	v_readlane_b32 s7, v254, 29
	s_getreg_b32 s100, hwreg(HW_REG_HW_ID, 0, 1)
	s_cmp_eq_u32 s100, 1
	s_cbranch_scc0 .Lstag_skip3
	s_sleep 127
